# v40 + code placement of straight-line code: FFN-up (x2) and w_in epilogue bodies shifted by 4 bytes, hot loop heads kept at 0 mod 8
# speedup vs baseline: 1.0025x; 1.0025x over previous
; __device__ __forceinline__ unsigned pk2(float lo, float hi) { f32x2_t v = {lo, hi}; bf16x2_t b = __builtin_convertvector(v, bf16x2_t); return __builtin_bit_cast(unsigned, b); }
; __device__ __forceinline__ float fast_sigmoid(float x) { return __builtin_amdgcn_rcpf(1.f + __expf(-x)); }
; __device__ __forceinline__ float row_ssq(const float* part, int pitch, int n4, int row, int fq) {
;     f32x4 v = (f32x4){0.f, 0.f, 0.f, 0.f};
;     if (fq < n4) v = *(const f32x4*)(part + (size_t)row * pitch + 4 * fq);
;     float s = (v[0] + v[1]) + (v[2] + v[3]);
;     s += __shfl_xor(s, 16); s += __shfl_xor(s, 32);
;     return s;
; }
;     __device__ __forceinline__ void operator()(const f32x4 (&acc)[2][2][4][2], const Unit& u, int wr, int wc, int fr, int fq) const {
;         const int row0 = u.pm * BM + wr * 64 + fr, col0 = u.pn * 128 + wc * 32 + 8 * fq;
; #pragma unroll
;         for (int ai = 0; ai < 2; ++ai)
; #pragma unroll
;             for (int m = 0; m < 4; ++m) {
;                 const int row = row0 + ai * HALF + m * 16;
;                 const float rs = rsqrtf(row_ssq(ssq, 16, 4, row, fq) * (1.f / 1024.f) + EPS);
;                 float r[8];
; #pragma unroll
;                 for (int n = 0; n < 2; ++n)
; #pragma unroll
;                     for (int e = 0; e < 4; ++e) { const float gv = acc[ai][0][m][n][e] * rs, uv = acc[ai][1][m][n][e] * rs; r[n * 4 + e] = gv * fast_sigmoid(gv) * uv; }
;                 u32x4 w; w.x = pk2(r[0], r[1]); w.y = pk2(r[2], r[3]); w.z = pk2(r[4], r[5]); w.w = pk2(r[6], r[7]);
;                 *(u32x4*)(O + (size_t)row * DFF + col0) = w;
.LBB0_168:
	s_nop 0
	v_and_b32_e32 v166, 48, v241
	v_lshl_add_u32 v166, v146, 6, v166
	v_add_u32_e32 v166, 0x24000, v166
	ds_read_b128 v[168:171], v166
	ds_read_b128 v[172:175], v166 offset:1024
	ds_read_b128 v[176:179], v166 offset:2048
	ds_read_b128 v[180:183], v166 offset:3072
	ds_read_b128 v[184:187], v166 offset:8192
	ds_read_b128 v[188:191], v166 offset:9216
	ds_read_b128 v[192:195], v166 offset:10240
	ds_read_b128 v[196:199], v166 offset:11264
	v_lshl_add_u32 v144, s44, 8, v146
	v_lshl_or_b32 v142, s4, 7, v148
	v_ashrrev_i32_e32 v143, 31, v142
	v_lshl_add_u64 v[142:143], v[142:143], 1, s[96:97]
	s_movk_i32 s4, 0x1600
	s_mov_b64 s[24:25], -1
	s_waitcnt lgkmcnt(7)
	v_add_f32_e32 v168, v169, v168
	v_add_f32_e32 v170, v170, v171
	v_add_f32_e32 v168, v168, v170
	v_mov_b32_e32 v169, v168
	s_waitcnt lgkmcnt(6)
	v_add_f32_e32 v172, v173, v172
	v_add_f32_e32 v174, v174, v175
	v_add_f32_e32 v172, v172, v174
	v_mov_b32_e32 v173, v172
	s_waitcnt lgkmcnt(5)
	v_add_f32_e32 v176, v177, v176
	v_add_f32_e32 v178, v178, v179
	v_add_f32_e32 v176, v176, v178
	v_mov_b32_e32 v177, v176
	s_waitcnt lgkmcnt(4)
	v_add_f32_e32 v180, v181, v180
	v_add_f32_e32 v182, v182, v183
	v_add_f32_e32 v180, v180, v182
	v_mov_b32_e32 v181, v180
	s_waitcnt lgkmcnt(3)
	v_add_f32_e32 v184, v185, v184
	v_add_f32_e32 v186, v186, v187
	v_add_f32_e32 v184, v184, v186
	v_mov_b32_e32 v185, v184
	s_waitcnt lgkmcnt(2)
	v_add_f32_e32 v188, v189, v188
	v_add_f32_e32 v190, v190, v191
	v_add_f32_e32 v188, v188, v190
	v_mov_b32_e32 v189, v188
	s_waitcnt lgkmcnt(1)
	v_add_f32_e32 v192, v193, v192
	v_add_f32_e32 v194, v194, v195
	v_add_f32_e32 v192, v192, v194
	v_mov_b32_e32 v193, v192
	s_waitcnt lgkmcnt(0)
	v_add_f32_e32 v196, v197, v196
	v_add_f32_e32 v198, v198, v199
	v_add_f32_e32 v196, v196, v198
	v_mov_b32_e32 v197, v196
	s_nop 1
	v_permlane16_swap_b32_e32 v168, v169
	v_permlane16_swap_b32_e32 v172, v173
	v_permlane16_swap_b32_e32 v176, v177
	v_permlane16_swap_b32_e32 v180, v181
	v_permlane16_swap_b32_e32 v184, v185
	v_permlane16_swap_b32_e32 v188, v189
	v_permlane16_swap_b32_e32 v192, v193
	v_permlane16_swap_b32_e32 v196, v197
	v_add_f32_e32 v168, v168, v169
	v_add_f32_e32 v172, v172, v173
	v_add_f32_e32 v176, v176, v177
	v_add_f32_e32 v180, v180, v181
	v_add_f32_e32 v184, v184, v185
	v_add_f32_e32 v188, v188, v189
	v_add_f32_e32 v192, v192, v193
	v_add_f32_e32 v196, v196, v197
	v_mov_b32_e32 v169, v168
	v_mov_b32_e32 v173, v172
	v_mov_b32_e32 v177, v176
	v_mov_b32_e32 v181, v180
	v_mov_b32_e32 v185, v184
	v_mov_b32_e32 v189, v188
	v_mov_b32_e32 v193, v192
	v_mov_b32_e32 v197, v196
	s_nop 1
	v_permlane32_swap_b32_e32 v168, v169
	v_permlane32_swap_b32_e32 v172, v173
	v_permlane32_swap_b32_e32 v176, v177
	v_permlane32_swap_b32_e32 v180, v181
	v_permlane32_swap_b32_e32 v184, v185
	v_permlane32_swap_b32_e32 v188, v189
	v_permlane32_swap_b32_e32 v192, v193
	v_permlane32_swap_b32_e32 v196, v197
	v_add_f32_e32 v168, v168, v169
	v_add_f32_e32 v172, v172, v173
	v_add_f32_e32 v176, v176, v177
	v_add_f32_e32 v180, v180, v181
	v_add_f32_e32 v184, v184, v185
	v_add_f32_e32 v188, v188, v189
	v_add_f32_e32 v192, v192, v193
	v_add_f32_e32 v196, v196, v197
	v_fmamk_f32 v168, v168, 0x3a800000, v239
	v_fmamk_f32 v172, v172, 0x3a800000, v239
	v_fmamk_f32 v176, v176, 0x3a800000, v239
	v_fmamk_f32 v180, v180, 0x3a800000, v239
	v_fmamk_f32 v184, v184, 0x3a800000, v239
	v_fmamk_f32 v188, v188, 0x3a800000, v239
	v_fmamk_f32 v192, v192, 0x3a800000, v239
	v_fmamk_f32 v196, v196, 0x3a800000, v239
	v_rsq_f32_e32 v158, v168
	v_rsq_f32_e32 v159, v172
	v_rsq_f32_e32 v160, v176
	v_rsq_f32_e32 v161, v180
	v_rsq_f32_e32 v162, v184
	v_rsq_f32_e32 v163, v188
	v_rsq_f32_e32 v164, v192
	v_rsq_f32_e32 v165, v196
	s_nop 0
	v_mov_b32_e32 v152, v158
	v_pk_mul_f32 v[126:127], v[126:127], v[152:153] op_sel_hi:[1,0]
	v_pk_mul_f32 v[118:119], v[118:119], v[152:153] op_sel_hi:[1,0]
	v_mul_f32_e32 v145, 0xbfb8aa3b, v126
	v_exp_f32_e32 v145, v145
	v_pk_mul_f32 v[120:121], v[120:121], v[152:153] op_sel_hi:[1,0]
	v_pk_mul_f32 v[122:123], v[122:123], v[152:153] op_sel_hi:[1,0]
	v_pk_mul_f32 v[114:115], v[114:115], v[152:153] op_sel_hi:[1,0]
	v_add_f32_e32 v145, 1.0, v145
	v_rcp_f32_e32 v154, v145
	v_mul_f32_e32 v145, 0xbfb8aa3b, v127
	v_exp_f32_e32 v145, v145
	v_pk_mul_f32 v[116:117], v[116:117], v[152:153] op_sel_hi:[1,0]
	v_add_f32_e32 v145, 1.0, v145
	v_rcp_f32_e32 v155, v145
	s_nop 0
	v_pk_mul_f32 v[126:127], v[126:127], v[154:155]
	s_nop 0
	v_pk_mul_f32 v[118:119], v[118:119], v[126:127]
	v_pk_mul_f32 v[126:127], v[128:129], v[152:153] op_sel_hi:[1,0]
	s_nop 0
	v_mul_f32_e32 v128, 0xbfb8aa3b, v126
	v_mul_f32_e32 v129, 0xbfb8aa3b, v127
	v_exp_f32_e32 v128, v128
	v_exp_f32_e32 v129, v129
	v_add_f32_e32 v128, 1.0, v128
	v_add_f32_e32 v129, 1.0, v129
	v_rcp_f32_e32 v128, v128
	v_rcp_f32_e32 v129, v129
	s_nop 0
	v_pk_mul_f32 v[126:127], v[126:127], v[128:129]
	s_nop 0
	v_pk_mul_f32 v[120:121], v[120:121], v[126:127]
	v_mul_f32_e32 v126, 0xbfb8aa3b, v122
	v_mul_f32_e32 v127, 0xbfb8aa3b, v123
	v_exp_f32_e32 v126, v126
	v_exp_f32_e32 v127, v127
	v_add_f32_e32 v126, 1.0, v126
	v_add_f32_e32 v127, 1.0, v127
	v_rcp_f32_e32 v126, v126
	v_rcp_f32_e32 v127, v127
	s_nop 0
	v_pk_mul_f32 v[122:123], v[122:123], v[126:127]
	s_nop 0
	v_pk_mul_f32 v[122:123], v[114:115], v[122:123]
	v_pk_mul_f32 v[114:115], v[124:125], v[152:153] op_sel_hi:[1,0]
	s_nop 0
	v_mul_f32_e32 v124, 0xbfb8aa3b, v114
	v_mul_f32_e32 v125, 0xbfb8aa3b, v115
	v_exp_f32_e32 v124, v124
	v_exp_f32_e32 v125, v125
	v_add_f32_e32 v124, 1.0, v124
	v_add_f32_e32 v125, 1.0, v125
	v_rcp_f32_e32 v124, v124
	v_rcp_f32_e32 v125, v125
	s_nop 0
	v_pk_mul_f32 v[114:115], v[114:115], v[124:125]
; __device__ __forceinline__ unsigned pk2(float lo, float hi) { f32x2_t v = {lo, hi}; bf16x2_t b = __builtin_convertvector(v, bf16x2_t); return __builtin_bit_cast(unsigned, b); }
; __device__ __forceinline__ float fast_sigmoid(float x) { return __builtin_amdgcn_rcpf(1.f + __expf(-x)); }
;     __device__ __forceinline__ void operator()(const f32x4 (&acc)[2][2][4][2], const Unit& u, int wr, int wc, int fr, int fq) const {
;     ...
;                 for (int n = 0; n < 2; ++n)
; #pragma unroll
;                     for (int e = 0; e < 4; ++e) { const float gv = acc[ai][0][m][n][e] * rs, uv = acc[ai][1][m][n][e] * rs; r[n * 4 + e] = gv * fast_sigmoid(gv) * uv; }
;                 u32x4 w; w.x = pk2(r[0], r[1]); w.y = pk2(r[2], r[3]); w.z = pk2(r[4], r[5]); w.w = pk2(r[6], r[7]);
;                 *(u32x4*)(O + (size_t)row * DFF + col0) = w;
	s_nop 0
	v_pk_mul_f32 v[124:125], v[116:117], v[114:115]
	v_cvt_pk_bf16_f32 v114, v118, v119
	v_cvt_pk_bf16_f32 v115, v120, v121
	v_cvt_pk_bf16_f32 v116, v122, v123
	v_cvt_pk_bf16_f32 v117, v124, v125
	v_mad_i64_i32 v[118:119], s[6:7], v144, s4, v[142:143]
	global_store_dwordx4 v[118:119], v[114:117], off
	s_nop 1
	v_or_b32_e32 v114, 16, v144
	v_mov_b32_e32 v116, v159
	v_pk_mul_f32 v[110:111], v[110:111], v[116:117] op_sel_hi:[1,0]
	v_pk_mul_f32 v[102:103], v[102:103], v[116:117] op_sel_hi:[1,0]
	v_mul_f32_e32 v115, 0xbfb8aa3b, v110
	v_exp_f32_e32 v115, v115
	v_pk_mul_f32 v[104:105], v[104:105], v[116:117] op_sel_hi:[1,0]
	v_pk_mul_f32 v[106:107], v[106:107], v[116:117] op_sel_hi:[1,0]
	v_pk_mul_f32 v[98:99], v[98:99], v[116:117] op_sel_hi:[1,0]
	v_add_f32_e32 v115, 1.0, v115
	v_rcp_f32_e32 v118, v115
	v_mul_f32_e32 v115, 0xbfb8aa3b, v111
	v_exp_f32_e32 v115, v115
	v_pk_mul_f32 v[100:101], v[100:101], v[116:117] op_sel_hi:[1,0]
	v_add_f32_e32 v115, 1.0, v115
	v_rcp_f32_e32 v119, v115
	s_nop 0
	v_pk_mul_f32 v[110:111], v[110:111], v[118:119]
	s_nop 0
	v_pk_mul_f32 v[102:103], v[102:103], v[110:111]
	v_pk_mul_f32 v[110:111], v[112:113], v[116:117] op_sel_hi:[1,0]
	s_nop 0
	v_mul_f32_e32 v112, 0xbfb8aa3b, v110
	v_mul_f32_e32 v113, 0xbfb8aa3b, v111
	v_exp_f32_e32 v112, v112
	v_exp_f32_e32 v113, v113
	v_add_f32_e32 v112, 1.0, v112
	v_add_f32_e32 v113, 1.0, v113
	v_rcp_f32_e32 v112, v112
	v_rcp_f32_e32 v113, v113
	s_nop 0
	v_pk_mul_f32 v[110:111], v[110:111], v[112:113]
	s_nop 0
	v_pk_mul_f32 v[104:105], v[104:105], v[110:111]
	v_mul_f32_e32 v110, 0xbfb8aa3b, v106
	v_mul_f32_e32 v111, 0xbfb8aa3b, v107
	v_exp_f32_e32 v110, v110
	v_exp_f32_e32 v111, v111
	v_add_f32_e32 v110, 1.0, v110
	v_add_f32_e32 v111, 1.0, v111
	v_rcp_f32_e32 v110, v110
	v_rcp_f32_e32 v111, v111
	s_nop 0
	v_pk_mul_f32 v[106:107], v[106:107], v[110:111]
	s_nop 0
	v_pk_mul_f32 v[106:107], v[98:99], v[106:107]
	v_pk_mul_f32 v[98:99], v[108:109], v[116:117] op_sel_hi:[1,0]
	s_nop 0
	v_mul_f32_e32 v108, 0xbfb8aa3b, v98
	v_mul_f32_e32 v109, 0xbfb8aa3b, v99
	v_exp_f32_e32 v108, v108
	v_exp_f32_e32 v109, v109
	v_add_f32_e32 v108, 1.0, v108
	v_add_f32_e32 v109, 1.0, v109
	v_rcp_f32_e32 v108, v108
	v_rcp_f32_e32 v109, v109
	s_nop 0
	v_pk_mul_f32 v[98:99], v[98:99], v[108:109]
	s_nop 0
	v_pk_mul_f32 v[108:109], v[100:101], v[98:99]
	v_cvt_pk_bf16_f32 v98, v102, v103
	v_cvt_pk_bf16_f32 v99, v104, v105
	v_cvt_pk_bf16_f32 v100, v106, v107
	v_cvt_pk_bf16_f32 v101, v108, v109
	v_mad_i64_i32 v[102:103], s[6:7], v114, s4, v[142:143]
	global_store_dwordx4 v[102:103], v[98:101], off
	s_nop 1
	v_or_b32_e32 v98, 32, v144
	v_mov_b32_e32 v100, v160
	v_pk_mul_f32 v[94:95], v[94:95], v[100:101] op_sel_hi:[1,0]
	v_pk_mul_f32 v[86:87], v[86:87], v[100:101] op_sel_hi:[1,0]
	v_mul_f32_e32 v99, 0xbfb8aa3b, v94
	v_exp_f32_e32 v99, v99
	v_pk_mul_f32 v[88:89], v[88:89], v[100:101] op_sel_hi:[1,0]
	v_pk_mul_f32 v[90:91], v[90:91], v[100:101] op_sel_hi:[1,0]
	v_pk_mul_f32 v[82:83], v[82:83], v[100:101] op_sel_hi:[1,0]
	v_add_f32_e32 v99, 1.0, v99
	v_rcp_f32_e32 v102, v99
	v_mul_f32_e32 v99, 0xbfb8aa3b, v95
	v_exp_f32_e32 v99, v99
	v_pk_mul_f32 v[84:85], v[84:85], v[100:101] op_sel_hi:[1,0]
	v_add_f32_e32 v99, 1.0, v99
	v_rcp_f32_e32 v103, v99
	s_nop 0
	v_pk_mul_f32 v[94:95], v[94:95], v[102:103]
	s_nop 0
	v_pk_mul_f32 v[86:87], v[86:87], v[94:95]
	v_pk_mul_f32 v[94:95], v[96:97], v[100:101] op_sel_hi:[1,0]
	s_nop 0
	v_mul_f32_e32 v96, 0xbfb8aa3b, v94
	v_mul_f32_e32 v97, 0xbfb8aa3b, v95
	v_exp_f32_e32 v96, v96
	v_exp_f32_e32 v97, v97
	v_add_f32_e32 v96, 1.0, v96
	v_add_f32_e32 v97, 1.0, v97
	v_rcp_f32_e32 v96, v96
	v_rcp_f32_e32 v97, v97
	s_nop 0
	v_pk_mul_f32 v[94:95], v[94:95], v[96:97]
	s_nop 0
	v_pk_mul_f32 v[88:89], v[88:89], v[94:95]
	v_mul_f32_e32 v94, 0xbfb8aa3b, v90
	v_mul_f32_e32 v95, 0xbfb8aa3b, v91
	v_exp_f32_e32 v94, v94
	v_exp_f32_e32 v95, v95
	v_add_f32_e32 v94, 1.0, v94
	v_add_f32_e32 v95, 1.0, v95
	v_rcp_f32_e32 v94, v94
	v_rcp_f32_e32 v95, v95
	s_nop 0
	v_pk_mul_f32 v[90:91], v[90:91], v[94:95]
	s_nop 0
	v_pk_mul_f32 v[90:91], v[82:83], v[90:91]
	v_pk_mul_f32 v[82:83], v[92:93], v[100:101] op_sel_hi:[1,0]
	s_nop 0
	v_mul_f32_e32 v92, 0xbfb8aa3b, v82
	v_mul_f32_e32 v93, 0xbfb8aa3b, v83
	v_exp_f32_e32 v92, v92
	v_exp_f32_e32 v93, v93
	v_add_f32_e32 v92, 1.0, v92
	v_add_f32_e32 v93, 1.0, v93
	v_rcp_f32_e32 v92, v92
	v_rcp_f32_e32 v93, v93
	s_nop 0
	v_pk_mul_f32 v[82:83], v[82:83], v[92:93]
	s_nop 0
	v_pk_mul_f32 v[92:93], v[84:85], v[82:83]
	v_cvt_pk_bf16_f32 v82, v86, v87
	v_cvt_pk_bf16_f32 v83, v88, v89
	v_cvt_pk_bf16_f32 v84, v90, v91
	v_cvt_pk_bf16_f32 v85, v92, v93
	v_mad_i64_i32 v[86:87], s[6:7], v98, s4, v[142:143]
	global_store_dwordx4 v[86:87], v[82:85], off
	s_nop 1
	v_or_b32_e32 v82, 48, v144
	v_mov_b32_e32 v84, v161
	v_pk_mul_f32 v[78:79], v[78:79], v[84:85] op_sel_hi:[1,0]
	v_pk_mul_f32 v[70:71], v[70:71], v[84:85] op_sel_hi:[1,0]
	v_mul_f32_e32 v83, 0xbfb8aa3b, v78
	v_exp_f32_e32 v83, v83
	v_pk_mul_f32 v[72:73], v[72:73], v[84:85] op_sel_hi:[1,0]
	v_pk_mul_f32 v[74:75], v[74:75], v[84:85] op_sel_hi:[1,0]
	v_pk_mul_f32 v[66:67], v[66:67], v[84:85] op_sel_hi:[1,0]
	v_add_f32_e32 v83, 1.0, v83
	v_rcp_f32_e32 v86, v83
	v_mul_f32_e32 v83, 0xbfb8aa3b, v79
	v_exp_f32_e32 v83, v83
	v_pk_mul_f32 v[68:69], v[68:69], v[84:85] op_sel_hi:[1,0]
	v_add_f32_e32 v83, 1.0, v83
	v_rcp_f32_e32 v87, v83
	s_nop 0
	v_pk_mul_f32 v[78:79], v[78:79], v[86:87]
	s_nop 0
	v_pk_mul_f32 v[70:71], v[70:71], v[78:79]
	v_pk_mul_f32 v[78:79], v[80:81], v[84:85] op_sel_hi:[1,0]
	s_nop 0
	v_mul_f32_e32 v80, 0xbfb8aa3b, v78
	v_mul_f32_e32 v81, 0xbfb8aa3b, v79
	v_exp_f32_e32 v80, v80
	v_exp_f32_e32 v81, v81
; __device__ __forceinline__ unsigned pk2(float lo, float hi) { f32x2_t v = {lo, hi}; bf16x2_t b = __builtin_convertvector(v, bf16x2_t); return __builtin_bit_cast(unsigned, b); }
; __device__ __forceinline__ float fast_sigmoid(float x) { return __builtin_amdgcn_rcpf(1.f + __expf(-x)); }
;     __device__ __forceinline__ void operator()(const f32x4 (&acc)[2][2][4][2], const Unit& u, int wr, int wc, int fr, int fq) const {
;     ...
;                 for (int n = 0; n < 2; ++n)
; #pragma unroll
;                     for (int e = 0; e < 4; ++e) { const float gv = acc[ai][0][m][n][e] * rs, uv = acc[ai][1][m][n][e] * rs; r[n * 4 + e] = gv * fast_sigmoid(gv) * uv; }
;                 u32x4 w; w.x = pk2(r[0], r[1]); w.y = pk2(r[2], r[3]); w.z = pk2(r[4], r[5]); w.w = pk2(r[6], r[7]);
;                 *(u32x4*)(O + (size_t)row * DFF + col0) = w;
	v_add_f32_e32 v80, 1.0, v80
	v_add_f32_e32 v81, 1.0, v81
	v_rcp_f32_e32 v80, v80
	v_rcp_f32_e32 v81, v81
	s_nop 0
	v_pk_mul_f32 v[78:79], v[78:79], v[80:81]
	s_nop 0
	v_pk_mul_f32 v[72:73], v[72:73], v[78:79]
	v_mul_f32_e32 v78, 0xbfb8aa3b, v74
	v_mul_f32_e32 v79, 0xbfb8aa3b, v75
	v_exp_f32_e32 v78, v78
	v_exp_f32_e32 v79, v79
	v_add_f32_e32 v78, 1.0, v78
	v_add_f32_e32 v79, 1.0, v79
	v_rcp_f32_e32 v78, v78
	v_rcp_f32_e32 v79, v79
	s_nop 0
	v_pk_mul_f32 v[74:75], v[74:75], v[78:79]
	s_nop 0
	v_pk_mul_f32 v[74:75], v[66:67], v[74:75]
	v_pk_mul_f32 v[66:67], v[76:77], v[84:85] op_sel_hi:[1,0]
	s_nop 0
	v_mul_f32_e32 v76, 0xbfb8aa3b, v66
	v_mul_f32_e32 v77, 0xbfb8aa3b, v67
	v_exp_f32_e32 v76, v76
	v_exp_f32_e32 v77, v77
	v_add_f32_e32 v76, 1.0, v76
	v_add_f32_e32 v77, 1.0, v77
	v_rcp_f32_e32 v76, v76
	v_rcp_f32_e32 v77, v77
	s_nop 0
	v_pk_mul_f32 v[66:67], v[66:67], v[76:77]
	s_nop 0
	v_pk_mul_f32 v[76:77], v[68:69], v[66:67]
	v_cvt_pk_bf16_f32 v66, v70, v71
	v_cvt_pk_bf16_f32 v67, v72, v73
	v_cvt_pk_bf16_f32 v68, v74, v75
	v_cvt_pk_bf16_f32 v69, v76, v77
	v_mad_i64_i32 v[70:71], s[6:7], v82, s4, v[142:143]
	global_store_dwordx4 v[70:71], v[66:69], off
	s_nop 1
	v_add_u32_e32 v66, 0x80, v144
	v_mov_b32_e32 v68, v162
	v_pk_mul_f32 v[62:63], v[62:63], v[68:69] op_sel_hi:[1,0]
	v_pk_mul_f32 v[54:55], v[54:55], v[68:69] op_sel_hi:[1,0]
	v_mul_f32_e32 v67, 0xbfb8aa3b, v62
	v_exp_f32_e32 v67, v67
	v_pk_mul_f32 v[56:57], v[56:57], v[68:69] op_sel_hi:[1,0]
	v_pk_mul_f32 v[58:59], v[58:59], v[68:69] op_sel_hi:[1,0]
	v_pk_mul_f32 v[50:51], v[50:51], v[68:69] op_sel_hi:[1,0]
	v_add_f32_e32 v67, 1.0, v67
	v_rcp_f32_e32 v70, v67
	v_mul_f32_e32 v67, 0xbfb8aa3b, v63
	v_exp_f32_e32 v67, v67
	v_pk_mul_f32 v[52:53], v[52:53], v[68:69] op_sel_hi:[1,0]
	v_add_f32_e32 v67, 1.0, v67
	v_rcp_f32_e32 v71, v67
	s_nop 0
	v_pk_mul_f32 v[62:63], v[62:63], v[70:71]
	s_nop 0
	v_pk_mul_f32 v[54:55], v[54:55], v[62:63]
	v_pk_mul_f32 v[62:63], v[64:65], v[68:69] op_sel_hi:[1,0]
	s_nop 0
	v_mul_f32_e32 v64, 0xbfb8aa3b, v62
	v_mul_f32_e32 v65, 0xbfb8aa3b, v63
	v_exp_f32_e32 v64, v64
	v_exp_f32_e32 v65, v65
	v_add_f32_e32 v64, 1.0, v64
	v_add_f32_e32 v65, 1.0, v65
	v_rcp_f32_e32 v64, v64
	v_rcp_f32_e32 v65, v65
	s_nop 0
	v_pk_mul_f32 v[62:63], v[62:63], v[64:65]
	s_nop 0
	v_pk_mul_f32 v[56:57], v[56:57], v[62:63]
	v_mul_f32_e32 v62, 0xbfb8aa3b, v58
	v_mul_f32_e32 v63, 0xbfb8aa3b, v59
	v_exp_f32_e32 v62, v62
	v_exp_f32_e32 v63, v63
	v_add_f32_e32 v62, 1.0, v62
	v_add_f32_e32 v63, 1.0, v63
	v_rcp_f32_e32 v62, v62
	v_rcp_f32_e32 v63, v63
	s_nop 0
	v_pk_mul_f32 v[58:59], v[58:59], v[62:63]
	s_nop 0
	v_pk_mul_f32 v[58:59], v[50:51], v[58:59]
	v_pk_mul_f32 v[50:51], v[60:61], v[68:69] op_sel_hi:[1,0]
	s_nop 0
	v_mul_f32_e32 v60, 0xbfb8aa3b, v50
	v_mul_f32_e32 v61, 0xbfb8aa3b, v51
	v_exp_f32_e32 v60, v60
	v_exp_f32_e32 v61, v61
	v_add_f32_e32 v60, 1.0, v60
	v_add_f32_e32 v61, 1.0, v61
	v_rcp_f32_e32 v60, v60
	v_rcp_f32_e32 v61, v61
	s_nop 0
	v_pk_mul_f32 v[50:51], v[50:51], v[60:61]
	s_nop 0
	v_pk_mul_f32 v[60:61], v[52:53], v[50:51]
	v_cvt_pk_bf16_f32 v50, v54, v55
	v_cvt_pk_bf16_f32 v51, v56, v57
	v_cvt_pk_bf16_f32 v52, v58, v59
	v_cvt_pk_bf16_f32 v53, v60, v61
	v_mad_i64_i32 v[54:55], s[6:7], v66, s4, v[142:143]
	global_store_dwordx4 v[54:55], v[50:53], off
	s_nop 1
	v_add_u32_e32 v50, 0x90, v144
	v_mov_b32_e32 v52, v163
	v_pk_mul_f32 v[46:47], v[46:47], v[52:53] op_sel_hi:[1,0]
	v_pk_mul_f32 v[38:39], v[38:39], v[52:53] op_sel_hi:[1,0]
	v_mul_f32_e32 v51, 0xbfb8aa3b, v46
	v_exp_f32_e32 v51, v51
	v_pk_mul_f32 v[40:41], v[40:41], v[52:53] op_sel_hi:[1,0]
	v_pk_mul_f32 v[42:43], v[42:43], v[52:53] op_sel_hi:[1,0]
	v_pk_mul_f32 v[34:35], v[34:35], v[52:53] op_sel_hi:[1,0]
	v_add_f32_e32 v51, 1.0, v51
	v_rcp_f32_e32 v54, v51
	v_mul_f32_e32 v51, 0xbfb8aa3b, v47
	v_exp_f32_e32 v51, v51
	v_pk_mul_f32 v[36:37], v[36:37], v[52:53] op_sel_hi:[1,0]
	v_add_f32_e32 v51, 1.0, v51
	v_rcp_f32_e32 v55, v51
	s_nop 0
	v_pk_mul_f32 v[46:47], v[46:47], v[54:55]
	s_nop 0
	v_pk_mul_f32 v[38:39], v[38:39], v[46:47]
	v_pk_mul_f32 v[46:47], v[48:49], v[52:53] op_sel_hi:[1,0]
	s_nop 0
	v_mul_f32_e32 v48, 0xbfb8aa3b, v46
	v_mul_f32_e32 v49, 0xbfb8aa3b, v47
	v_exp_f32_e32 v48, v48
	v_exp_f32_e32 v49, v49
	v_add_f32_e32 v48, 1.0, v48
	v_add_f32_e32 v49, 1.0, v49
	v_rcp_f32_e32 v48, v48
	v_rcp_f32_e32 v49, v49
	s_nop 0
	v_pk_mul_f32 v[46:47], v[46:47], v[48:49]
	s_nop 0
	v_pk_mul_f32 v[40:41], v[40:41], v[46:47]
	v_mul_f32_e32 v46, 0xbfb8aa3b, v42
	v_mul_f32_e32 v47, 0xbfb8aa3b, v43
	v_exp_f32_e32 v46, v46
	v_exp_f32_e32 v47, v47
	v_add_f32_e32 v46, 1.0, v46
	v_add_f32_e32 v47, 1.0, v47
	v_rcp_f32_e32 v46, v46
	v_rcp_f32_e32 v47, v47
	s_nop 0
	v_pk_mul_f32 v[42:43], v[42:43], v[46:47]
	s_nop 0
	v_pk_mul_f32 v[42:43], v[34:35], v[42:43]
	v_pk_mul_f32 v[34:35], v[44:45], v[52:53] op_sel_hi:[1,0]
	s_nop 0
	v_mul_f32_e32 v44, 0xbfb8aa3b, v34
; __device__ __forceinline__ unsigned pk2(float lo, float hi) { f32x2_t v = {lo, hi}; bf16x2_t b = __builtin_convertvector(v, bf16x2_t); return __builtin_bit_cast(unsigned, b); }
; __device__ __forceinline__ float fast_sigmoid(float x) { return __builtin_amdgcn_rcpf(1.f + __expf(-x)); }
; #define PG8_BAR __builtin_amdgcn_s_barrier()
; template <class Epi>
; __device__ __forceinline__ void gemm_phase(LAS unsigned char* lds, int wave_s, const Gemm g, const StaticOrder S, const Epi E) {
;     ...
;         if (wr == 0) PG8_BAR;
;         E(acc, cur, wr, wc, fr, fq);
;         if (!has_next) break;
; #pragma unroll
;         for (int a = 0; a < 2; ++a)
; #pragma unroll
;             for (int b = 0; b < 2; ++b)
; #pragma unroll
;                 for (int m = 0; m < 4; ++m)
; #pragma unroll
;                     for (int n = 0; n < 2; ++n) acc[a][b][m][n] = (f32x4){0.f, 0.f, 0.f, 0.f};
;         cur = nxt; cA = nA; cB = nB; ++ui;
;         if (wr == 1) PG8_BAR;
;     __device__ __forceinline__ void operator()(const f32x4 (&acc)[2][2][4][2], const Unit& u, int wr, int wc, int fr, int fq) const {
;     ...
;                 for (int n = 0; n < 2; ++n)
; #pragma unroll
;                     for (int e = 0; e < 4; ++e) { const float gv = acc[ai][0][m][n][e] * rs, uv = acc[ai][1][m][n][e] * rs; r[n * 4 + e] = gv * fast_sigmoid(gv) * uv; }
;                 u32x4 w; w.x = pk2(r[0], r[1]); w.y = pk2(r[2], r[3]); w.z = pk2(r[4], r[5]); w.w = pk2(r[6], r[7]);
;                 *(u32x4*)(O + (size_t)row * DFF + col0) = w;
	v_mul_f32_e32 v45, 0xbfb8aa3b, v35
	v_exp_f32_e32 v44, v44
	v_exp_f32_e32 v45, v45
	v_add_f32_e32 v44, 1.0, v44
	v_add_f32_e32 v45, 1.0, v45
	v_rcp_f32_e32 v44, v44
	v_rcp_f32_e32 v45, v45
	s_nop 0
	v_pk_mul_f32 v[34:35], v[34:35], v[44:45]
	s_nop 0
	v_pk_mul_f32 v[44:45], v[36:37], v[34:35]
	v_cvt_pk_bf16_f32 v34, v38, v39
	v_cvt_pk_bf16_f32 v35, v40, v41
	v_cvt_pk_bf16_f32 v36, v42, v43
	v_cvt_pk_bf16_f32 v37, v44, v45
	v_mad_i64_i32 v[38:39], s[6:7], v50, s4, v[142:143]
	global_store_dwordx4 v[38:39], v[34:37], off
	s_nop 1
	v_add_u32_e32 v34, 0xa0, v144
	v_mov_b32_e32 v36, v164
	v_pk_mul_f32 v[30:31], v[30:31], v[36:37] op_sel_hi:[1,0]
	v_pk_mul_f32 v[22:23], v[22:23], v[36:37] op_sel_hi:[1,0]
	v_mul_f32_e32 v35, 0xbfb8aa3b, v30
	v_exp_f32_e32 v35, v35
	v_pk_mul_f32 v[24:25], v[24:25], v[36:37] op_sel_hi:[1,0]
	v_pk_mul_f32 v[26:27], v[26:27], v[36:37] op_sel_hi:[1,0]
	v_pk_mul_f32 v[18:19], v[18:19], v[36:37] op_sel_hi:[1,0]
	v_add_f32_e32 v35, 1.0, v35
	v_rcp_f32_e32 v38, v35
	v_mul_f32_e32 v35, 0xbfb8aa3b, v31
	v_exp_f32_e32 v35, v35
	v_pk_mul_f32 v[20:21], v[20:21], v[36:37] op_sel_hi:[1,0]
	v_add_f32_e32 v35, 1.0, v35
	v_rcp_f32_e32 v39, v35
	s_nop 0
	v_pk_mul_f32 v[30:31], v[30:31], v[38:39]
	s_nop 0
	v_pk_mul_f32 v[22:23], v[22:23], v[30:31]
	v_pk_mul_f32 v[30:31], v[32:33], v[36:37] op_sel_hi:[1,0]
	s_nop 0
	v_mul_f32_e32 v32, 0xbfb8aa3b, v30
	v_mul_f32_e32 v33, 0xbfb8aa3b, v31
	v_exp_f32_e32 v32, v32
	v_exp_f32_e32 v33, v33
	v_add_f32_e32 v32, 1.0, v32
	v_add_f32_e32 v33, 1.0, v33
	v_rcp_f32_e32 v32, v32
	v_rcp_f32_e32 v33, v33
	s_nop 0
	v_pk_mul_f32 v[30:31], v[30:31], v[32:33]
	s_nop 0
	v_pk_mul_f32 v[24:25], v[24:25], v[30:31]
	v_mul_f32_e32 v30, 0xbfb8aa3b, v26
	v_mul_f32_e32 v31, 0xbfb8aa3b, v27
	v_exp_f32_e32 v30, v30
	v_exp_f32_e32 v31, v31
	v_add_f32_e32 v30, 1.0, v30
	v_add_f32_e32 v31, 1.0, v31
	v_rcp_f32_e32 v30, v30
	v_rcp_f32_e32 v31, v31
	s_nop 0
	v_pk_mul_f32 v[26:27], v[26:27], v[30:31]
	s_nop 0
	v_pk_mul_f32 v[26:27], v[18:19], v[26:27]
	v_pk_mul_f32 v[18:19], v[28:29], v[36:37] op_sel_hi:[1,0]
	s_nop 0
	v_mul_f32_e32 v28, 0xbfb8aa3b, v18
	v_mul_f32_e32 v29, 0xbfb8aa3b, v19
	v_exp_f32_e32 v28, v28
	v_exp_f32_e32 v29, v29
	v_add_f32_e32 v28, 1.0, v28
	v_add_f32_e32 v29, 1.0, v29
	v_rcp_f32_e32 v28, v28
	v_rcp_f32_e32 v29, v29
	s_nop 0
	v_pk_mul_f32 v[18:19], v[18:19], v[28:29]
	s_nop 0
	v_pk_mul_f32 v[28:29], v[20:21], v[18:19]
	v_cvt_pk_bf16_f32 v18, v22, v23
	v_cvt_pk_bf16_f32 v19, v24, v25
	v_cvt_pk_bf16_f32 v20, v26, v27
	v_cvt_pk_bf16_f32 v21, v28, v29
	v_mad_i64_i32 v[22:23], s[6:7], v34, s4, v[142:143]
	global_store_dwordx4 v[22:23], v[18:21], off
	s_nop 1
	v_add_u32_e32 v18, 0xb0, v144
	v_mov_b32_e32 v20, v165
	v_pk_mul_f32 v[14:15], v[14:15], v[20:21] op_sel_hi:[1,0]
	v_pk_mul_f32 v[6:7], v[6:7], v[20:21] op_sel_hi:[1,0]
	v_mul_f32_e32 v19, 0xbfb8aa3b, v14
	v_exp_f32_e32 v19, v19
	v_pk_mul_f32 v[8:9], v[8:9], v[20:21] op_sel_hi:[1,0]
	v_pk_mul_f32 v[10:11], v[10:11], v[20:21] op_sel_hi:[1,0]
	v_pk_mul_f32 v[2:3], v[2:3], v[20:21] op_sel_hi:[1,0]
	v_add_f32_e32 v19, 1.0, v19
	v_rcp_f32_e32 v22, v19
	v_mul_f32_e32 v19, 0xbfb8aa3b, v15
	v_exp_f32_e32 v19, v19
	v_pk_mul_f32 v[4:5], v[4:5], v[20:21] op_sel_hi:[1,0]
	s_andn2_b64 vcc, exec, s[0:1]
	v_add_f32_e32 v19, 1.0, v19
	v_rcp_f32_e32 v23, v19
	s_nop 0
	v_pk_mul_f32 v[14:15], v[14:15], v[22:23]
	s_nop 0
	v_pk_mul_f32 v[6:7], v[6:7], v[14:15]
	v_pk_mul_f32 v[14:15], v[16:17], v[20:21] op_sel_hi:[1,0]
	s_nop 0
	v_mul_f32_e32 v16, 0xbfb8aa3b, v14
	v_mul_f32_e32 v17, 0xbfb8aa3b, v15
	v_exp_f32_e32 v16, v16
	v_exp_f32_e32 v17, v17
	v_add_f32_e32 v16, 1.0, v16
	v_add_f32_e32 v17, 1.0, v17
	v_rcp_f32_e32 v16, v16
	v_rcp_f32_e32 v17, v17
	s_nop 0
	v_pk_mul_f32 v[14:15], v[14:15], v[16:17]
	s_nop 0
	v_pk_mul_f32 v[8:9], v[8:9], v[14:15]
	v_mul_f32_e32 v14, 0xbfb8aa3b, v10
	v_mul_f32_e32 v15, 0xbfb8aa3b, v11
	v_exp_f32_e32 v14, v14
	v_exp_f32_e32 v15, v15
	v_add_f32_e32 v14, 1.0, v14
	v_add_f32_e32 v15, 1.0, v15
	v_rcp_f32_e32 v14, v14
	v_rcp_f32_e32 v15, v15
	s_nop 0
	v_pk_mul_f32 v[10:11], v[10:11], v[14:15]
	s_nop 0
	v_pk_mul_f32 v[10:11], v[2:3], v[10:11]
	v_pk_mul_f32 v[2:3], v[12:13], v[20:21] op_sel_hi:[1,0]
	s_nop 0
	v_mul_f32_e32 v12, 0xbfb8aa3b, v2
	v_mul_f32_e32 v13, 0xbfb8aa3b, v3
	v_exp_f32_e32 v12, v12
	v_exp_f32_e32 v13, v13
	v_add_f32_e32 v12, 1.0, v12
	v_add_f32_e32 v13, 1.0, v13
	v_rcp_f32_e32 v12, v12
	v_rcp_f32_e32 v13, v13
	s_nop 0
	v_pk_mul_f32 v[2:3], v[2:3], v[12:13]
	s_nop 0
	v_pk_mul_f32 v[12:13], v[4:5], v[2:3]
	v_cvt_pk_bf16_f32 v2, v6, v7
	v_cvt_pk_bf16_f32 v3, v8, v9
	v_cvt_pk_bf16_f32 v4, v10, v11
	v_cvt_pk_bf16_f32 v5, v12, v13
	v_mad_i64_i32 v[6:7], s[6:7], v18, s4, v[142:143]
	global_store_dwordx4 v[6:7], v[2:5], off
	s_cbranch_vccnz .LBB0_161
	s_andn2_b64 vcc, exec, s[12:13]
	s_cbranch_vccnz .LBB0_160
	s_barrier
	s_branch .LBB0_160

; template <class Epi>
; __device__ __forceinline__ void gemm_phase(LAS unsigned char* lds, int wave_s, const Gemm g, const StaticOrder S, const Epi E) {
;     ...
;         const bool has_next = S.next(ui + 1, nxt);
;         const char* nA = has_next ? (const char*)g.A + (size_t)nxt.pm * tstepA : cA; const char* nB = has_next ? (const char*)g.Bt + (size_t)nxt.pn * tstepB : cB;
;     ...
; #pragma unroll
;         for (int a = 0; a < 2; ++a)
; #pragma unroll
;             for (int b = 0; b < 2; ++b)
; #pragma unroll
;                 for (int m = 0; m < 4; ++m)
; #pragma unroll
;                     for (int n = 0; n < 2; ++n) acc[a][b][m][n] = (f32x4){0.f, 0.f, 0.f, 0.f};
;         cur = nxt; cA = nA; cB = nB; ++ui;
.LBB0_238:
	s_and_b64 vcc, exec, s[46:47]
	s_mov_b64 s[50:51], s[14:15]
	s_cbranch_vccnz .LBB0_240
	s_mul_i32 s7, s29, 0x160000
	v_readlane_b32 s10, v255, 19
	s_mul_hi_i32 s6, s29, 0x160000
	v_readlane_b32 s11, v255, 20
	s_add_u32 s50, s10, s7
	s_addc_u32 s51, s11, s6
.LBB0_240:
	s_add_u32 s10, s14, 0x100
	v_mov_b32_e32 v2, 0
	s_addc_u32 s11, s15, 0
	s_mov_b32 s34, -2
	v_mov_b32_e32 v246, v2
	v_mov_b32_e32 v247, v2
	v_mov_b32_e32 v248, v2
	v_mov_b32_e32 v249, v2
	v_mov_b32_e32 v3, v2
	v_mov_b32_e32 v4, v2
	v_mfma_f32_32x32x16_bf16 v[18:33], v[246:249], v[246:249], 0
	v_mov_b32_e32 v5, v2
	v_mov_b32_e32 v6, v2
	v_mfma_f32_32x32x16_bf16 v[34:49], v[246:249], v[246:249], 0
	v_mov_b32_e32 v7, v2
	v_mov_b32_e32 v8, v2
	v_mfma_f32_32x32x16_bf16 v[50:65], v[246:249], v[246:249], 0
	v_mov_b32_e32 v9, v2
	v_mov_b32_e32 v10, v2
	v_mfma_f32_32x32x16_bf16 v[66:81], v[246:249], v[246:249], 0
	v_mov_b32_e32 v11, v2
	v_mov_b32_e32 v12, v2
	v_mfma_f32_32x32x16_bf16 v[82:97], v[246:249], v[246:249], 0
	v_mov_b32_e32 v13, v2
	v_mov_b32_e32 v14, v2
	v_mfma_f32_32x32x16_bf16 v[98:113], v[246:249], v[246:249], 0
	v_mov_b32_e32 v15, v2
	v_mov_b32_e32 v16, v2
	v_mfma_f32_32x32x16_bf16 v[114:129], v[246:249], v[246:249], 0
	v_mov_b32_e32 v17, v2
	s_nop 0
.LBB0_241:
	s_cmp_eq_u32 s34, 36
	s_cbranch_scc0 .Lpre_f1d_skip
	s_mov_b64 s[100:101], s[38:39]
	v_readlane_b32 s98, v250, 49
	v_readlane_b32 s99, v250, 50
	v_lshl_add_u32 v243, s31, 8, v160
	v_lshl_or_b32 v246, s4, 8, v162
	v_lshl_add_u32 v243, v243, 10, v246
	v_lshlrev_b32_e32 v243, 1, v243
	s_nop 1
	global_load_dwordx4 v[226:229], v243, s[100:101]
	global_load_dwordx4 v[230:233], v243, s[98:99]
	global_load_dwordx4 v[234:237], v243, s[100:101] offset:256
	global_load_dwordx4 v[242:245], v243, s[98:99] offset:256

; __device__ __forceinline__ float row_ssq(const float* part, int pitch, int n4, int row, int fq) {
;     f32x4 v = (f32x4){0.f, 0.f, 0.f, 0.f};
;     if (fq < n4) v = *(const f32x4*)(part + (size_t)row * pitch + 4 * fq);
;     float s = (v[0] + v[1]) + (v[2] + v[3]);
;     s += __shfl_xor(s, 16); s += __shfl_xor(s, 32);
;     return s;
; }
;     __device__ __forceinline__ void operator()(const f32x4 (&acc)[2][2][4][2], const Unit& u, int wr, int wc, int fr, int fq) const {
;     ...
;         float rsv[2][4];
; #pragma unroll
;         for (int ai = 0; ai < 2; ++ai)
; #pragma unroll
;             for (int m = 0; m < 4; ++m) rsv[ai][m] = ssq_in ? rsqrtf(row_ssq(ssq_in, in_pitch, in_n4, row0 + ai * HALF + m * 16, fq) * inv_k + EPS) : 1.f;
.LBB0_331:
	s_nop 0
	v_readlane_b32 s0, v252, 23
	v_readlane_b32 s1, v252, 24
	v_lshl_add_u32 v156, s4, 8, v139
	v_mov_b32_e32 v163, 1.0
	v_cndmask_b32_e64 v0, 0, 1, s[0:1]
	v_cmp_ne_u32_e64 s[50:51], 1, v0
	s_andn2_b64 vcc, exec, s[0:1]
	v_ashrrev_i32_e32 v157, 31, v156
	v_mov_b32_e32 v164, 1.0
	v_mov_b32_e32 v162, 1.0
	v_mov_b32_e32 v161, 1.0
	v_mov_b32_e32 v160, 1.0
	v_mov_b32_e32 v155, 1.0
	v_mov_b32_e32 v153, 1.0
	v_mov_b32_e32 v151, 1.0
	v_or_b32_e32 v154, 16, v156
	v_or_b32_e32 v152, 32, v156
	v_or_b32_e32 v150, 48, v156
	v_add_u32_e32 v148, 0x80, v156
	v_ashrrev_i32_e32 v149, 31, v148
	s_cbranch_vccnz .Lrsv_win_done
	v_and_b32_e32 v166, 48, v241
	v_lshl_add_u32 v166, v139, 6, v166
	v_add_u32_e32 v166, 0x24000, v166
	ds_read_b128 v[168:171], v166
	ds_read_b128 v[172:175], v166 offset:1024
	ds_read_b128 v[176:179], v166 offset:2048
	ds_read_b128 v[180:183], v166 offset:3072
	ds_read_b128 v[184:187], v166 offset:8192
	ds_read_b128 v[188:191], v166 offset:9216
	ds_read_b128 v[192:195], v166 offset:10240
	ds_read_b128 v[196:199], v166 offset:11264
	s_waitcnt lgkmcnt(7)
	v_add_f32_e32 v168, v169, v168
	v_add_f32_e32 v170, v170, v171
	v_add_f32_e32 v168, v168, v170
	v_mov_b32_e32 v169, v168
	s_waitcnt lgkmcnt(6)
	v_add_f32_e32 v172, v173, v172
	v_add_f32_e32 v174, v174, v175
	v_add_f32_e32 v172, v172, v174
	v_mov_b32_e32 v173, v172
	s_waitcnt lgkmcnt(5)
	v_add_f32_e32 v176, v177, v176
	v_add_f32_e32 v178, v178, v179
	v_add_f32_e32 v176, v176, v178
	v_mov_b32_e32 v177, v176
	s_waitcnt lgkmcnt(4)
	v_add_f32_e32 v180, v181, v180
	v_add_f32_e32 v182, v182, v183
	v_add_f32_e32 v180, v180, v182
	v_mov_b32_e32 v181, v180
	s_waitcnt lgkmcnt(3)
	v_add_f32_e32 v184, v185, v184
	v_add_f32_e32 v186, v186, v187
	v_add_f32_e32 v184, v184, v186
	v_mov_b32_e32 v185, v184
	s_waitcnt lgkmcnt(2)
	v_add_f32_e32 v188, v189, v188
	v_add_f32_e32 v190, v190, v191
	v_add_f32_e32 v188, v188, v190
	v_mov_b32_e32 v189, v188
	s_waitcnt lgkmcnt(1)
	v_add_f32_e32 v192, v193, v192
	v_add_f32_e32 v194, v194, v195
	v_add_f32_e32 v192, v192, v194
	v_mov_b32_e32 v193, v192
	s_waitcnt lgkmcnt(0)
	v_add_f32_e32 v196, v197, v196
	v_add_f32_e32 v198, v198, v199
	v_add_f32_e32 v196, v196, v198
	v_mov_b32_e32 v197, v196
	s_nop 1
	v_permlane16_swap_b32_e32 v168, v169
	v_permlane16_swap_b32_e32 v172, v173
	v_permlane16_swap_b32_e32 v176, v177
	v_permlane16_swap_b32_e32 v180, v181
	v_permlane16_swap_b32_e32 v184, v185
	v_permlane16_swap_b32_e32 v188, v189
	v_permlane16_swap_b32_e32 v192, v193
	v_permlane16_swap_b32_e32 v196, v197
	v_add_f32_e32 v168, v168, v169
	v_add_f32_e32 v172, v172, v173
	v_add_f32_e32 v176, v176, v177
	v_add_f32_e32 v180, v180, v181
	v_add_f32_e32 v184, v184, v185
	v_add_f32_e32 v188, v188, v189
	v_add_f32_e32 v192, v192, v193
	v_add_f32_e32 v196, v196, v197
	v_mov_b32_e32 v169, v168
	v_mov_b32_e32 v173, v172
	v_mov_b32_e32 v177, v176
	v_mov_b32_e32 v181, v180
	v_mov_b32_e32 v185, v184
	v_mov_b32_e32 v189, v188
	v_mov_b32_e32 v193, v192
	v_mov_b32_e32 v197, v196
	s_nop 1
	v_permlane32_swap_b32_e32 v168, v169
	v_permlane32_swap_b32_e32 v172, v173
	v_permlane32_swap_b32_e32 v176, v177
	v_permlane32_swap_b32_e32 v180, v181
	v_permlane32_swap_b32_e32 v184, v185
	v_permlane32_swap_b32_e32 v188, v189
	v_permlane32_swap_b32_e32 v192, v193
	v_permlane32_swap_b32_e32 v196, v197
	v_add_f32_e32 v168, v168, v169
	v_add_f32_e32 v172, v172, v173
	v_add_f32_e32 v176, v176, v177
	v_add_f32_e32 v180, v180, v181
	v_add_f32_e32 v184, v184, v185
	v_add_f32_e32 v188, v188, v189
	v_add_f32_e32 v192, v192, v193
	v_add_f32_e32 v196, v196, v197
	v_fmamk_f32 v168, v168, 0x3a800000, v239
	v_fmamk_f32 v172, v172, 0x3a800000, v239
	v_fmamk_f32 v176, v176, 0x3a800000, v239
	v_fmamk_f32 v180, v180, 0x3a800000, v239
	v_fmamk_f32 v184, v184, 0x3a800000, v239
	v_fmamk_f32 v188, v188, 0x3a800000, v239
	v_fmamk_f32 v192, v192, 0x3a800000, v239
	v_fmamk_f32 v196, v196, 0x3a800000, v239
	v_rsq_f32_e32 v164, v168
	v_rsq_f32_e32 v163, v172
	v_rsq_f32_e32 v162, v176
	v_rsq_f32_e32 v161, v180
	v_rsq_f32_e32 v160, v184
	v_rsq_f32_e32 v155, v188
	v_rsq_f32_e32 v153, v192
	v_rsq_f32_e32 v151, v196
	s_nop 0

; __device__ __forceinline__ unsigned pk2(float lo, float hi) { f32x2_t v = {lo, hi}; bf16x2_t b = __builtin_convertvector(v, bf16x2_t); return __builtin_bit_cast(unsigned, b); }
; __device__ __forceinline__ float fast_sigmoid(float x) { return __builtin_amdgcn_rcpf(1.f + __expf(-x)); }
; __device__ __forceinline__ float row_ssq(const float* part, int pitch, int n4, int row, int fq) {
;     f32x4 v = (f32x4){0.f, 0.f, 0.f, 0.f};
;     if (fq < n4) v = *(const f32x4*)(part + (size_t)row * pitch + 4 * fq);
;     float s = (v[0] + v[1]) + (v[2] + v[3]);
;     s += __shfl_xor(s, 16); s += __shfl_xor(s, 32);
;     return s;
; }
;     __device__ __forceinline__ void operator()(const f32x4 (&acc)[2][2][4][2], const Unit& u, int wr, int wc, int fr, int fq) const {
;         const int row0 = u.pm * BM + wr * 64 + fr, col0 = u.pn * 128 + wc * 32 + 8 * fq;
; #pragma unroll
;         for (int ai = 0; ai < 2; ++ai)
; #pragma unroll
;             for (int m = 0; m < 4; ++m) {
;                 const int row = row0 + ai * HALF + m * 16;
;                 const float rs = rsqrtf(row_ssq(ssq, 16, 4, row, fq) * (1.f / 1024.f) + EPS);
;                 float r[8];
; #pragma unroll
;                 for (int n = 0; n < 2; ++n)
; #pragma unroll
;                     for (int e = 0; e < 4; ++e) { const float gv = acc[ai][0][m][n][e] * rs, uv = acc[ai][1][m][n][e] * rs; r[n * 4 + e] = gv * fast_sigmoid(gv) * uv; }
;                 u32x4 w; w.x = pk2(r[0], r[1]); w.y = pk2(r[2], r[3]); w.z = pk2(r[4], r[5]); w.w = pk2(r[6], r[7]);
;                 *(u32x4*)(O + (size_t)row * DFF + col0) = w;
.LBB0_1154:
	s_nop 0
	v_and_b32_e32 v166, 48, v241
	v_lshl_add_u32 v166, v146, 6, v166
	v_add_u32_e32 v166, 0x24000, v166
	ds_read_b128 v[168:171], v166
	ds_read_b128 v[172:175], v166 offset:1024
	ds_read_b128 v[176:179], v166 offset:2048
	ds_read_b128 v[180:183], v166 offset:3072
	ds_read_b128 v[184:187], v166 offset:8192
	ds_read_b128 v[188:191], v166 offset:9216
	ds_read_b128 v[192:195], v166 offset:10240
	ds_read_b128 v[196:199], v166 offset:11264
	v_lshl_add_u32 v144, s39, 8, v146
	v_lshl_or_b32 v142, s4, 7, v148
	v_ashrrev_i32_e32 v143, 31, v142
	v_lshl_add_u64 v[142:143], v[142:143], 1, s[96:97]
	s_movk_i32 s4, 0x1600
	s_mov_b64 s[22:23], -1
	s_waitcnt lgkmcnt(7)
	v_add_f32_e32 v168, v169, v168
	v_add_f32_e32 v170, v170, v171
	v_add_f32_e32 v168, v168, v170
	v_mov_b32_e32 v169, v168
	s_waitcnt lgkmcnt(6)
	v_add_f32_e32 v172, v173, v172
	v_add_f32_e32 v174, v174, v175
	v_add_f32_e32 v172, v172, v174
	v_mov_b32_e32 v173, v172
	s_waitcnt lgkmcnt(5)
	v_add_f32_e32 v176, v177, v176
	v_add_f32_e32 v178, v178, v179
	v_add_f32_e32 v176, v176, v178
	v_mov_b32_e32 v177, v176
	s_waitcnt lgkmcnt(4)
	v_add_f32_e32 v180, v181, v180
	v_add_f32_e32 v182, v182, v183
	v_add_f32_e32 v180, v180, v182
	v_mov_b32_e32 v181, v180
	s_waitcnt lgkmcnt(3)
	v_add_f32_e32 v184, v185, v184
	v_add_f32_e32 v186, v186, v187
	v_add_f32_e32 v184, v184, v186
	v_mov_b32_e32 v185, v184
	s_waitcnt lgkmcnt(2)
	v_add_f32_e32 v188, v189, v188
	v_add_f32_e32 v190, v190, v191
	v_add_f32_e32 v188, v188, v190
	v_mov_b32_e32 v189, v188
	s_waitcnt lgkmcnt(1)
	v_add_f32_e32 v192, v193, v192
	v_add_f32_e32 v194, v194, v195
	v_add_f32_e32 v192, v192, v194
	v_mov_b32_e32 v193, v192
	s_waitcnt lgkmcnt(0)
	v_add_f32_e32 v196, v197, v196
	v_add_f32_e32 v198, v198, v199
	v_add_f32_e32 v196, v196, v198
	v_mov_b32_e32 v197, v196
	s_nop 1
	v_permlane16_swap_b32_e32 v168, v169
	v_permlane16_swap_b32_e32 v172, v173
	v_permlane16_swap_b32_e32 v176, v177
	v_permlane16_swap_b32_e32 v180, v181
	v_permlane16_swap_b32_e32 v184, v185
	v_permlane16_swap_b32_e32 v188, v189
	v_permlane16_swap_b32_e32 v192, v193
	v_permlane16_swap_b32_e32 v196, v197
	v_add_f32_e32 v168, v168, v169
	v_add_f32_e32 v172, v172, v173
	v_add_f32_e32 v176, v176, v177
	v_add_f32_e32 v180, v180, v181
	v_add_f32_e32 v184, v184, v185
	v_add_f32_e32 v188, v188, v189
	v_add_f32_e32 v192, v192, v193
	v_add_f32_e32 v196, v196, v197
	v_mov_b32_e32 v169, v168
	v_mov_b32_e32 v173, v172
	v_mov_b32_e32 v177, v176
	v_mov_b32_e32 v181, v180
	v_mov_b32_e32 v185, v184
	v_mov_b32_e32 v189, v188
	v_mov_b32_e32 v193, v192
	v_mov_b32_e32 v197, v196
	s_nop 1
	v_permlane32_swap_b32_e32 v168, v169
	v_permlane32_swap_b32_e32 v172, v173
	v_permlane32_swap_b32_e32 v176, v177
	v_permlane32_swap_b32_e32 v180, v181
	v_permlane32_swap_b32_e32 v184, v185
	v_permlane32_swap_b32_e32 v188, v189
	v_permlane32_swap_b32_e32 v192, v193
	v_permlane32_swap_b32_e32 v196, v197
	v_add_f32_e32 v168, v168, v169
	v_add_f32_e32 v172, v172, v173
	v_add_f32_e32 v176, v176, v177
	v_add_f32_e32 v180, v180, v181
	v_add_f32_e32 v184, v184, v185
	v_add_f32_e32 v188, v188, v189
	v_add_f32_e32 v192, v192, v193
	v_add_f32_e32 v196, v196, v197
	v_fmamk_f32 v168, v168, 0x3a800000, v239
	v_fmamk_f32 v172, v172, 0x3a800000, v239
	v_fmamk_f32 v176, v176, 0x3a800000, v239
	v_fmamk_f32 v180, v180, 0x3a800000, v239
	v_fmamk_f32 v184, v184, 0x3a800000, v239
	v_fmamk_f32 v188, v188, 0x3a800000, v239
	v_fmamk_f32 v192, v192, 0x3a800000, v239
	v_fmamk_f32 v196, v196, 0x3a800000, v239
	v_rsq_f32_e32 v158, v168
	v_rsq_f32_e32 v159, v172
	v_rsq_f32_e32 v160, v176
	v_rsq_f32_e32 v161, v180
	v_rsq_f32_e32 v162, v184
	v_rsq_f32_e32 v163, v188
	v_rsq_f32_e32 v164, v192
	v_rsq_f32_e32 v165, v196
	s_nop 0
	v_mov_b32_e32 v152, v158
	v_pk_mul_f32 v[126:127], v[126:127], v[152:153] op_sel_hi:[1,0]
	v_pk_mul_f32 v[118:119], v[118:119], v[152:153] op_sel_hi:[1,0]
	v_mul_f32_e32 v145, 0xbfb8aa3b, v126
	v_exp_f32_e32 v145, v145
	v_pk_mul_f32 v[120:121], v[120:121], v[152:153] op_sel_hi:[1,0]
	v_pk_mul_f32 v[122:123], v[122:123], v[152:153] op_sel_hi:[1,0]
	v_pk_mul_f32 v[114:115], v[114:115], v[152:153] op_sel_hi:[1,0]
	v_add_f32_e32 v145, 1.0, v145
	v_rcp_f32_e32 v154, v145
	v_mul_f32_e32 v145, 0xbfb8aa3b, v127
	v_exp_f32_e32 v145, v145
	v_pk_mul_f32 v[116:117], v[116:117], v[152:153] op_sel_hi:[1,0]
	v_add_f32_e32 v145, 1.0, v145
	v_rcp_f32_e32 v155, v145
	s_nop 0
	v_pk_mul_f32 v[126:127], v[126:127], v[154:155]
	s_nop 0
	v_pk_mul_f32 v[118:119], v[118:119], v[126:127]
	v_pk_mul_f32 v[126:127], v[128:129], v[152:153] op_sel_hi:[1,0]
	s_nop 0
	v_mul_f32_e32 v128, 0xbfb8aa3b, v126
	v_mul_f32_e32 v129, 0xbfb8aa3b, v127
	v_exp_f32_e32 v128, v128
	v_exp_f32_e32 v129, v129
	v_add_f32_e32 v128, 1.0, v128
	v_add_f32_e32 v129, 1.0, v129
	v_rcp_f32_e32 v128, v128
	v_rcp_f32_e32 v129, v129
	s_nop 0
	v_pk_mul_f32 v[126:127], v[126:127], v[128:129]
	s_nop 0
	v_pk_mul_f32 v[120:121], v[120:121], v[126:127]
	v_mul_f32_e32 v126, 0xbfb8aa3b, v122
	v_mul_f32_e32 v127, 0xbfb8aa3b, v123
	v_exp_f32_e32 v126, v126
	v_exp_f32_e32 v127, v127
	v_add_f32_e32 v126, 1.0, v126
	v_add_f32_e32 v127, 1.0, v127
	v_rcp_f32_e32 v126, v126
	v_rcp_f32_e32 v127, v127
	s_nop 0
	v_pk_mul_f32 v[122:123], v[122:123], v[126:127]
	s_nop 0
	v_pk_mul_f32 v[122:123], v[114:115], v[122:123]
	v_pk_mul_f32 v[114:115], v[124:125], v[152:153] op_sel_hi:[1,0]
	s_nop 0
	v_mul_f32_e32 v124, 0xbfb8aa3b, v114
	v_mul_f32_e32 v125, 0xbfb8aa3b, v115
	v_exp_f32_e32 v124, v124
	v_exp_f32_e32 v125, v125
	v_add_f32_e32 v124, 1.0, v124
	v_add_f32_e32 v125, 1.0, v125
	v_rcp_f32_e32 v124, v124
	v_rcp_f32_e32 v125, v125
	s_nop 0
	v_pk_mul_f32 v[114:115], v[114:115], v[124:125]
; __device__ __forceinline__ unsigned pk2(float lo, float hi) { f32x2_t v = {lo, hi}; bf16x2_t b = __builtin_convertvector(v, bf16x2_t); return __builtin_bit_cast(unsigned, b); }
; __device__ __forceinline__ float fast_sigmoid(float x) { return __builtin_amdgcn_rcpf(1.f + __expf(-x)); }
;     __device__ __forceinline__ void operator()(const f32x4 (&acc)[2][2][4][2], const Unit& u, int wr, int wc, int fr, int fq) const {
;     ...
;                 for (int n = 0; n < 2; ++n)
; #pragma unroll
;                     for (int e = 0; e < 4; ++e) { const float gv = acc[ai][0][m][n][e] * rs, uv = acc[ai][1][m][n][e] * rs; r[n * 4 + e] = gv * fast_sigmoid(gv) * uv; }
;                 u32x4 w; w.x = pk2(r[0], r[1]); w.y = pk2(r[2], r[3]); w.z = pk2(r[4], r[5]); w.w = pk2(r[6], r[7]);
;                 *(u32x4*)(O + (size_t)row * DFF + col0) = w;
	s_nop 0
	v_pk_mul_f32 v[124:125], v[116:117], v[114:115]
	v_cvt_pk_bf16_f32 v114, v118, v119
	v_cvt_pk_bf16_f32 v115, v120, v121
	v_cvt_pk_bf16_f32 v116, v122, v123
	v_cvt_pk_bf16_f32 v117, v124, v125
	v_mad_i64_i32 v[118:119], s[6:7], v144, s4, v[142:143]
	global_store_dwordx4 v[118:119], v[114:117], off
	s_nop 1
	v_or_b32_e32 v114, 16, v144
	v_mov_b32_e32 v116, v159
	v_pk_mul_f32 v[110:111], v[110:111], v[116:117] op_sel_hi:[1,0]
	v_pk_mul_f32 v[102:103], v[102:103], v[116:117] op_sel_hi:[1,0]
	v_mul_f32_e32 v115, 0xbfb8aa3b, v110
	v_exp_f32_e32 v115, v115
	v_pk_mul_f32 v[104:105], v[104:105], v[116:117] op_sel_hi:[1,0]
	v_pk_mul_f32 v[106:107], v[106:107], v[116:117] op_sel_hi:[1,0]
	v_pk_mul_f32 v[98:99], v[98:99], v[116:117] op_sel_hi:[1,0]
	v_add_f32_e32 v115, 1.0, v115
	v_rcp_f32_e32 v118, v115
	v_mul_f32_e32 v115, 0xbfb8aa3b, v111
	v_exp_f32_e32 v115, v115
	v_pk_mul_f32 v[100:101], v[100:101], v[116:117] op_sel_hi:[1,0]
	v_add_f32_e32 v115, 1.0, v115
	v_rcp_f32_e32 v119, v115
	s_nop 0
	v_pk_mul_f32 v[110:111], v[110:111], v[118:119]
	s_nop 0
	v_pk_mul_f32 v[102:103], v[102:103], v[110:111]
	v_pk_mul_f32 v[110:111], v[112:113], v[116:117] op_sel_hi:[1,0]
	s_nop 0
	v_mul_f32_e32 v112, 0xbfb8aa3b, v110
	v_mul_f32_e32 v113, 0xbfb8aa3b, v111
	v_exp_f32_e32 v112, v112
	v_exp_f32_e32 v113, v113
	v_add_f32_e32 v112, 1.0, v112
	v_add_f32_e32 v113, 1.0, v113
	v_rcp_f32_e32 v112, v112
	v_rcp_f32_e32 v113, v113
	s_nop 0
	v_pk_mul_f32 v[110:111], v[110:111], v[112:113]
	s_nop 0
	v_pk_mul_f32 v[104:105], v[104:105], v[110:111]
	v_mul_f32_e32 v110, 0xbfb8aa3b, v106
	v_mul_f32_e32 v111, 0xbfb8aa3b, v107
	v_exp_f32_e32 v110, v110
	v_exp_f32_e32 v111, v111
	v_add_f32_e32 v110, 1.0, v110
	v_add_f32_e32 v111, 1.0, v111
	v_rcp_f32_e32 v110, v110
	v_rcp_f32_e32 v111, v111
	s_nop 0
	v_pk_mul_f32 v[106:107], v[106:107], v[110:111]
	s_nop 0
	v_pk_mul_f32 v[106:107], v[98:99], v[106:107]
	v_pk_mul_f32 v[98:99], v[108:109], v[116:117] op_sel_hi:[1,0]
	s_nop 0
	v_mul_f32_e32 v108, 0xbfb8aa3b, v98
	v_mul_f32_e32 v109, 0xbfb8aa3b, v99
	v_exp_f32_e32 v108, v108
	v_exp_f32_e32 v109, v109
	v_add_f32_e32 v108, 1.0, v108
	v_add_f32_e32 v109, 1.0, v109
	v_rcp_f32_e32 v108, v108
	v_rcp_f32_e32 v109, v109
	s_nop 0
	v_pk_mul_f32 v[98:99], v[98:99], v[108:109]
	s_nop 0
	v_pk_mul_f32 v[108:109], v[100:101], v[98:99]
	v_cvt_pk_bf16_f32 v98, v102, v103
	v_cvt_pk_bf16_f32 v99, v104, v105
	v_cvt_pk_bf16_f32 v100, v106, v107
	v_cvt_pk_bf16_f32 v101, v108, v109
	v_mad_i64_i32 v[102:103], s[6:7], v114, s4, v[142:143]
	global_store_dwordx4 v[102:103], v[98:101], off
	s_nop 1
	v_or_b32_e32 v98, 32, v144
	v_mov_b32_e32 v100, v160
	v_pk_mul_f32 v[94:95], v[94:95], v[100:101] op_sel_hi:[1,0]
	v_pk_mul_f32 v[86:87], v[86:87], v[100:101] op_sel_hi:[1,0]
	v_mul_f32_e32 v99, 0xbfb8aa3b, v94
	v_exp_f32_e32 v99, v99
	v_pk_mul_f32 v[88:89], v[88:89], v[100:101] op_sel_hi:[1,0]
	v_pk_mul_f32 v[90:91], v[90:91], v[100:101] op_sel_hi:[1,0]
	v_pk_mul_f32 v[82:83], v[82:83], v[100:101] op_sel_hi:[1,0]
	v_add_f32_e32 v99, 1.0, v99
	v_rcp_f32_e32 v102, v99
	v_mul_f32_e32 v99, 0xbfb8aa3b, v95
	v_exp_f32_e32 v99, v99
	v_pk_mul_f32 v[84:85], v[84:85], v[100:101] op_sel_hi:[1,0]
	v_add_f32_e32 v99, 1.0, v99
	v_rcp_f32_e32 v103, v99
	s_nop 0
	v_pk_mul_f32 v[94:95], v[94:95], v[102:103]
	s_nop 0
	v_pk_mul_f32 v[86:87], v[86:87], v[94:95]
	v_pk_mul_f32 v[94:95], v[96:97], v[100:101] op_sel_hi:[1,0]
	s_nop 0
	v_mul_f32_e32 v96, 0xbfb8aa3b, v94
	v_mul_f32_e32 v97, 0xbfb8aa3b, v95
	v_exp_f32_e32 v96, v96
	v_exp_f32_e32 v97, v97
	v_add_f32_e32 v96, 1.0, v96
	v_add_f32_e32 v97, 1.0, v97
	v_rcp_f32_e32 v96, v96
	v_rcp_f32_e32 v97, v97
	s_nop 0
	v_pk_mul_f32 v[94:95], v[94:95], v[96:97]
	s_nop 0
	v_pk_mul_f32 v[88:89], v[88:89], v[94:95]
	v_mul_f32_e32 v94, 0xbfb8aa3b, v90
	v_mul_f32_e32 v95, 0xbfb8aa3b, v91
	v_exp_f32_e32 v94, v94
	v_exp_f32_e32 v95, v95
	v_add_f32_e32 v94, 1.0, v94
	v_add_f32_e32 v95, 1.0, v95
	v_rcp_f32_e32 v94, v94
	v_rcp_f32_e32 v95, v95
	s_nop 0
	v_pk_mul_f32 v[90:91], v[90:91], v[94:95]
	s_nop 0
	v_pk_mul_f32 v[90:91], v[82:83], v[90:91]
	v_pk_mul_f32 v[82:83], v[92:93], v[100:101] op_sel_hi:[1,0]
	s_nop 0
	v_mul_f32_e32 v92, 0xbfb8aa3b, v82
	v_mul_f32_e32 v93, 0xbfb8aa3b, v83
	v_exp_f32_e32 v92, v92
	v_exp_f32_e32 v93, v93
	v_add_f32_e32 v92, 1.0, v92
	v_add_f32_e32 v93, 1.0, v93
	v_rcp_f32_e32 v92, v92
	v_rcp_f32_e32 v93, v93
	s_nop 0
	v_pk_mul_f32 v[82:83], v[82:83], v[92:93]
	s_nop 0
	v_pk_mul_f32 v[92:93], v[84:85], v[82:83]
	v_cvt_pk_bf16_f32 v82, v86, v87
	v_cvt_pk_bf16_f32 v83, v88, v89
	v_cvt_pk_bf16_f32 v84, v90, v91
	v_cvt_pk_bf16_f32 v85, v92, v93
	v_mad_i64_i32 v[86:87], s[6:7], v98, s4, v[142:143]
	global_store_dwordx4 v[86:87], v[82:85], off
	s_nop 1
	v_or_b32_e32 v82, 48, v144
	v_mov_b32_e32 v84, v161
	v_pk_mul_f32 v[78:79], v[78:79], v[84:85] op_sel_hi:[1,0]
	v_pk_mul_f32 v[70:71], v[70:71], v[84:85] op_sel_hi:[1,0]
	v_mul_f32_e32 v83, 0xbfb8aa3b, v78
	v_exp_f32_e32 v83, v83
	v_pk_mul_f32 v[72:73], v[72:73], v[84:85] op_sel_hi:[1,0]
	v_pk_mul_f32 v[74:75], v[74:75], v[84:85] op_sel_hi:[1,0]
	v_pk_mul_f32 v[66:67], v[66:67], v[84:85] op_sel_hi:[1,0]
	v_add_f32_e32 v83, 1.0, v83
	v_rcp_f32_e32 v86, v83
	v_mul_f32_e32 v83, 0xbfb8aa3b, v79
	v_exp_f32_e32 v83, v83
	v_pk_mul_f32 v[68:69], v[68:69], v[84:85] op_sel_hi:[1,0]
	v_add_f32_e32 v83, 1.0, v83
	v_rcp_f32_e32 v87, v83
	s_nop 0
	v_pk_mul_f32 v[78:79], v[78:79], v[86:87]
	s_nop 0
	v_pk_mul_f32 v[70:71], v[70:71], v[78:79]
	v_pk_mul_f32 v[78:79], v[80:81], v[84:85] op_sel_hi:[1,0]
	s_nop 0
	v_mul_f32_e32 v80, 0xbfb8aa3b, v78
	v_mul_f32_e32 v81, 0xbfb8aa3b, v79
	v_exp_f32_e32 v80, v80
	v_exp_f32_e32 v81, v81
; __device__ __forceinline__ unsigned pk2(float lo, float hi) { f32x2_t v = {lo, hi}; bf16x2_t b = __builtin_convertvector(v, bf16x2_t); return __builtin_bit_cast(unsigned, b); }
; __device__ __forceinline__ float fast_sigmoid(float x) { return __builtin_amdgcn_rcpf(1.f + __expf(-x)); }
;     __device__ __forceinline__ void operator()(const f32x4 (&acc)[2][2][4][2], const Unit& u, int wr, int wc, int fr, int fq) const {
;     ...
;                 for (int n = 0; n < 2; ++n)
; #pragma unroll
;                     for (int e = 0; e < 4; ++e) { const float gv = acc[ai][0][m][n][e] * rs, uv = acc[ai][1][m][n][e] * rs; r[n * 4 + e] = gv * fast_sigmoid(gv) * uv; }
;                 u32x4 w; w.x = pk2(r[0], r[1]); w.y = pk2(r[2], r[3]); w.z = pk2(r[4], r[5]); w.w = pk2(r[6], r[7]);
;                 *(u32x4*)(O + (size_t)row * DFF + col0) = w;
	v_add_f32_e32 v80, 1.0, v80
	v_add_f32_e32 v81, 1.0, v81
	v_rcp_f32_e32 v80, v80
	v_rcp_f32_e32 v81, v81
	s_nop 0
	v_pk_mul_f32 v[78:79], v[78:79], v[80:81]
	s_nop 0
	v_pk_mul_f32 v[72:73], v[72:73], v[78:79]
	v_mul_f32_e32 v78, 0xbfb8aa3b, v74
	v_mul_f32_e32 v79, 0xbfb8aa3b, v75
	v_exp_f32_e32 v78, v78
	v_exp_f32_e32 v79, v79
	v_add_f32_e32 v78, 1.0, v78
	v_add_f32_e32 v79, 1.0, v79
	v_rcp_f32_e32 v78, v78
	v_rcp_f32_e32 v79, v79
	s_nop 0
	v_pk_mul_f32 v[74:75], v[74:75], v[78:79]
	s_nop 0
	v_pk_mul_f32 v[74:75], v[66:67], v[74:75]
	v_pk_mul_f32 v[66:67], v[76:77], v[84:85] op_sel_hi:[1,0]
	s_nop 0
	v_mul_f32_e32 v76, 0xbfb8aa3b, v66
	v_mul_f32_e32 v77, 0xbfb8aa3b, v67
	v_exp_f32_e32 v76, v76
	v_exp_f32_e32 v77, v77
	v_add_f32_e32 v76, 1.0, v76
	v_add_f32_e32 v77, 1.0, v77
	v_rcp_f32_e32 v76, v76
	v_rcp_f32_e32 v77, v77
	s_nop 0
	v_pk_mul_f32 v[66:67], v[66:67], v[76:77]
	s_nop 0
	v_pk_mul_f32 v[76:77], v[68:69], v[66:67]
	v_cvt_pk_bf16_f32 v66, v70, v71
	v_cvt_pk_bf16_f32 v67, v72, v73
	v_cvt_pk_bf16_f32 v68, v74, v75
	v_cvt_pk_bf16_f32 v69, v76, v77
	v_mad_i64_i32 v[70:71], s[6:7], v82, s4, v[142:143]
	global_store_dwordx4 v[70:71], v[66:69], off
	s_nop 1
	v_add_u32_e32 v66, 0x80, v144
	v_mov_b32_e32 v68, v162
	v_pk_mul_f32 v[62:63], v[62:63], v[68:69] op_sel_hi:[1,0]
	v_pk_mul_f32 v[54:55], v[54:55], v[68:69] op_sel_hi:[1,0]
	v_mul_f32_e32 v67, 0xbfb8aa3b, v62
	v_exp_f32_e32 v67, v67
	v_pk_mul_f32 v[56:57], v[56:57], v[68:69] op_sel_hi:[1,0]
	v_pk_mul_f32 v[58:59], v[58:59], v[68:69] op_sel_hi:[1,0]
	v_pk_mul_f32 v[50:51], v[50:51], v[68:69] op_sel_hi:[1,0]
	v_add_f32_e32 v67, 1.0, v67
	v_rcp_f32_e32 v70, v67
	v_mul_f32_e32 v67, 0xbfb8aa3b, v63
	v_exp_f32_e32 v67, v67
	v_pk_mul_f32 v[52:53], v[52:53], v[68:69] op_sel_hi:[1,0]
	v_add_f32_e32 v67, 1.0, v67
	v_rcp_f32_e32 v71, v67
	s_nop 0
	v_pk_mul_f32 v[62:63], v[62:63], v[70:71]
	s_nop 0
	v_pk_mul_f32 v[54:55], v[54:55], v[62:63]
	v_pk_mul_f32 v[62:63], v[64:65], v[68:69] op_sel_hi:[1,0]
	s_nop 0
	v_mul_f32_e32 v64, 0xbfb8aa3b, v62
	v_mul_f32_e32 v65, 0xbfb8aa3b, v63
	v_exp_f32_e32 v64, v64
	v_exp_f32_e32 v65, v65
	v_add_f32_e32 v64, 1.0, v64
	v_add_f32_e32 v65, 1.0, v65
	v_rcp_f32_e32 v64, v64
	v_rcp_f32_e32 v65, v65
	s_nop 0
	v_pk_mul_f32 v[62:63], v[62:63], v[64:65]
	s_nop 0
	v_pk_mul_f32 v[56:57], v[56:57], v[62:63]
	v_mul_f32_e32 v62, 0xbfb8aa3b, v58
	v_mul_f32_e32 v63, 0xbfb8aa3b, v59
	v_exp_f32_e32 v62, v62
	v_exp_f32_e32 v63, v63
	v_add_f32_e32 v62, 1.0, v62
	v_add_f32_e32 v63, 1.0, v63
	v_rcp_f32_e32 v62, v62
	v_rcp_f32_e32 v63, v63
	s_nop 0
	v_pk_mul_f32 v[58:59], v[58:59], v[62:63]
	s_nop 0
	v_pk_mul_f32 v[58:59], v[50:51], v[58:59]
	v_pk_mul_f32 v[50:51], v[60:61], v[68:69] op_sel_hi:[1,0]
	s_nop 0
	v_mul_f32_e32 v60, 0xbfb8aa3b, v50
	v_mul_f32_e32 v61, 0xbfb8aa3b, v51
	v_exp_f32_e32 v60, v60
	v_exp_f32_e32 v61, v61
	v_add_f32_e32 v60, 1.0, v60
	v_add_f32_e32 v61, 1.0, v61
	v_rcp_f32_e32 v60, v60
	v_rcp_f32_e32 v61, v61
	s_nop 0
	v_pk_mul_f32 v[50:51], v[50:51], v[60:61]
	s_nop 0
	v_pk_mul_f32 v[60:61], v[52:53], v[50:51]
	v_cvt_pk_bf16_f32 v50, v54, v55
	v_cvt_pk_bf16_f32 v51, v56, v57
	v_cvt_pk_bf16_f32 v52, v58, v59
	v_cvt_pk_bf16_f32 v53, v60, v61
	v_mad_i64_i32 v[54:55], s[6:7], v66, s4, v[142:143]
	global_store_dwordx4 v[54:55], v[50:53], off
	s_nop 1
	v_add_u32_e32 v50, 0x90, v144
	v_mov_b32_e32 v52, v163
	v_pk_mul_f32 v[46:47], v[46:47], v[52:53] op_sel_hi:[1,0]
	v_pk_mul_f32 v[38:39], v[38:39], v[52:53] op_sel_hi:[1,0]
	v_mul_f32_e32 v51, 0xbfb8aa3b, v46
	v_exp_f32_e32 v51, v51
	v_pk_mul_f32 v[40:41], v[40:41], v[52:53] op_sel_hi:[1,0]
	v_pk_mul_f32 v[42:43], v[42:43], v[52:53] op_sel_hi:[1,0]
	v_pk_mul_f32 v[34:35], v[34:35], v[52:53] op_sel_hi:[1,0]
	v_add_f32_e32 v51, 1.0, v51
	v_rcp_f32_e32 v54, v51
	v_mul_f32_e32 v51, 0xbfb8aa3b, v47
	v_exp_f32_e32 v51, v51
	v_pk_mul_f32 v[36:37], v[36:37], v[52:53] op_sel_hi:[1,0]
	v_add_f32_e32 v51, 1.0, v51
	v_rcp_f32_e32 v55, v51
	s_nop 0
	v_pk_mul_f32 v[46:47], v[46:47], v[54:55]
	s_nop 0
	v_pk_mul_f32 v[38:39], v[38:39], v[46:47]
	v_pk_mul_f32 v[46:47], v[48:49], v[52:53] op_sel_hi:[1,0]
	s_nop 0
	v_mul_f32_e32 v48, 0xbfb8aa3b, v46
	v_mul_f32_e32 v49, 0xbfb8aa3b, v47
	v_exp_f32_e32 v48, v48
	v_exp_f32_e32 v49, v49
	v_add_f32_e32 v48, 1.0, v48
	v_add_f32_e32 v49, 1.0, v49
	v_rcp_f32_e32 v48, v48
	v_rcp_f32_e32 v49, v49
	s_nop 0
	v_pk_mul_f32 v[46:47], v[46:47], v[48:49]
	s_nop 0
	v_pk_mul_f32 v[40:41], v[40:41], v[46:47]
	v_mul_f32_e32 v46, 0xbfb8aa3b, v42
	v_mul_f32_e32 v47, 0xbfb8aa3b, v43
	v_exp_f32_e32 v46, v46
	v_exp_f32_e32 v47, v47
	v_add_f32_e32 v46, 1.0, v46
	v_add_f32_e32 v47, 1.0, v47
	v_rcp_f32_e32 v46, v46
	v_rcp_f32_e32 v47, v47
	s_nop 0
	v_pk_mul_f32 v[42:43], v[42:43], v[46:47]
	s_nop 0
	v_pk_mul_f32 v[42:43], v[34:35], v[42:43]
	v_pk_mul_f32 v[34:35], v[44:45], v[52:53] op_sel_hi:[1,0]
	s_nop 0
	v_mul_f32_e32 v44, 0xbfb8aa3b, v34
; __device__ __forceinline__ unsigned pk2(float lo, float hi) { f32x2_t v = {lo, hi}; bf16x2_t b = __builtin_convertvector(v, bf16x2_t); return __builtin_bit_cast(unsigned, b); }
; __device__ __forceinline__ float fast_sigmoid(float x) { return __builtin_amdgcn_rcpf(1.f + __expf(-x)); }
; #define PG8_BAR __builtin_amdgcn_s_barrier()
; template <class Epi>
; __device__ __forceinline__ void gemm_phase(LAS unsigned char* lds, int wave_s, const Gemm g, const StaticOrder S, const Epi E) {
;     ...
;         cur = nxt; cA = nA; cB = nB; ++ui;
;         if (wr == 1) PG8_BAR;
;     __device__ __forceinline__ void operator()(const f32x4 (&acc)[2][2][4][2], const Unit& u, int wr, int wc, int fr, int fq) const {
;     ...
;             for (int m = 0; m < 4; ++m) {
;                 const int row = row0 + ai * HALF + m * 16;
;                 const float rs = rsqrtf(row_ssq(ssq, 16, 4, row, fq) * (1.f / 1024.f) + EPS);
;                 float r[8];
; #pragma unroll
;                 for (int n = 0; n < 2; ++n)
; #pragma unroll
;                     for (int e = 0; e < 4; ++e) { const float gv = acc[ai][0][m][n][e] * rs, uv = acc[ai][1][m][n][e] * rs; r[n * 4 + e] = gv * fast_sigmoid(gv) * uv; }
;                 u32x4 w; w.x = pk2(r[0], r[1]); w.y = pk2(r[2], r[3]); w.z = pk2(r[4], r[5]); w.w = pk2(r[6], r[7]);
;                 *(u32x4*)(O + (size_t)row * DFF + col0) = w;
;             }
	v_mul_f32_e32 v45, 0xbfb8aa3b, v35
	v_exp_f32_e32 v44, v44
	v_exp_f32_e32 v45, v45
	v_add_f32_e32 v44, 1.0, v44
	v_add_f32_e32 v45, 1.0, v45
	v_rcp_f32_e32 v44, v44
	v_rcp_f32_e32 v45, v45
	s_nop 0
	v_pk_mul_f32 v[34:35], v[34:35], v[44:45]
	s_nop 0
	v_pk_mul_f32 v[44:45], v[36:37], v[34:35]
	v_cvt_pk_bf16_f32 v34, v38, v39
	v_cvt_pk_bf16_f32 v35, v40, v41
	v_cvt_pk_bf16_f32 v36, v42, v43
	v_cvt_pk_bf16_f32 v37, v44, v45
	v_mad_i64_i32 v[38:39], s[6:7], v50, s4, v[142:143]
	global_store_dwordx4 v[38:39], v[34:37], off
	s_nop 1
	v_add_u32_e32 v34, 0xa0, v144
	v_mov_b32_e32 v36, v164
	v_pk_mul_f32 v[30:31], v[30:31], v[36:37] op_sel_hi:[1,0]
	v_pk_mul_f32 v[22:23], v[22:23], v[36:37] op_sel_hi:[1,0]
	v_mul_f32_e32 v35, 0xbfb8aa3b, v30
	v_exp_f32_e32 v35, v35
	v_pk_mul_f32 v[24:25], v[24:25], v[36:37] op_sel_hi:[1,0]
	v_pk_mul_f32 v[26:27], v[26:27], v[36:37] op_sel_hi:[1,0]
	v_pk_mul_f32 v[18:19], v[18:19], v[36:37] op_sel_hi:[1,0]
	v_add_f32_e32 v35, 1.0, v35
	v_rcp_f32_e32 v38, v35
	v_mul_f32_e32 v35, 0xbfb8aa3b, v31
	v_exp_f32_e32 v35, v35
	v_pk_mul_f32 v[20:21], v[20:21], v[36:37] op_sel_hi:[1,0]
	v_add_f32_e32 v35, 1.0, v35
	v_rcp_f32_e32 v39, v35
	s_nop 0
	v_pk_mul_f32 v[30:31], v[30:31], v[38:39]
	s_nop 0
	v_pk_mul_f32 v[22:23], v[22:23], v[30:31]
	v_pk_mul_f32 v[30:31], v[32:33], v[36:37] op_sel_hi:[1,0]
	s_nop 0
	v_mul_f32_e32 v32, 0xbfb8aa3b, v30
	v_mul_f32_e32 v33, 0xbfb8aa3b, v31
	v_exp_f32_e32 v32, v32
	v_exp_f32_e32 v33, v33
	v_add_f32_e32 v32, 1.0, v32
	v_add_f32_e32 v33, 1.0, v33
	v_rcp_f32_e32 v32, v32
	v_rcp_f32_e32 v33, v33
	s_nop 0
	v_pk_mul_f32 v[30:31], v[30:31], v[32:33]
	s_nop 0
	v_pk_mul_f32 v[24:25], v[24:25], v[30:31]
	v_mul_f32_e32 v30, 0xbfb8aa3b, v26
	v_mul_f32_e32 v31, 0xbfb8aa3b, v27
	v_exp_f32_e32 v30, v30
	v_exp_f32_e32 v31, v31
	v_add_f32_e32 v30, 1.0, v30
	v_add_f32_e32 v31, 1.0, v31
	v_rcp_f32_e32 v30, v30
	v_rcp_f32_e32 v31, v31
	s_nop 0
	v_pk_mul_f32 v[26:27], v[26:27], v[30:31]
	s_nop 0
	v_pk_mul_f32 v[26:27], v[18:19], v[26:27]
	v_pk_mul_f32 v[18:19], v[28:29], v[36:37] op_sel_hi:[1,0]
	s_nop 0
	v_mul_f32_e32 v28, 0xbfb8aa3b, v18
	v_mul_f32_e32 v29, 0xbfb8aa3b, v19
	v_exp_f32_e32 v28, v28
	v_exp_f32_e32 v29, v29
	v_add_f32_e32 v28, 1.0, v28
	v_add_f32_e32 v29, 1.0, v29
	v_rcp_f32_e32 v28, v28
	v_rcp_f32_e32 v29, v29
	s_nop 0
	v_pk_mul_f32 v[18:19], v[18:19], v[28:29]
	s_nop 0
	v_pk_mul_f32 v[28:29], v[20:21], v[18:19]
	v_cvt_pk_bf16_f32 v18, v22, v23
	v_cvt_pk_bf16_f32 v19, v24, v25
	v_cvt_pk_bf16_f32 v20, v26, v27
	v_cvt_pk_bf16_f32 v21, v28, v29
	v_mad_i64_i32 v[22:23], s[6:7], v34, s4, v[142:143]
	global_store_dwordx4 v[22:23], v[18:21], off
	s_nop 1
	v_add_u32_e32 v18, 0xb0, v144
	v_mov_b32_e32 v20, v165
	v_pk_mul_f32 v[14:15], v[14:15], v[20:21] op_sel_hi:[1,0]
	v_pk_mul_f32 v[6:7], v[6:7], v[20:21] op_sel_hi:[1,0]
	v_mul_f32_e32 v19, 0xbfb8aa3b, v14
	v_exp_f32_e32 v19, v19
	v_pk_mul_f32 v[8:9], v[8:9], v[20:21] op_sel_hi:[1,0]
	v_pk_mul_f32 v[10:11], v[10:11], v[20:21] op_sel_hi:[1,0]
	v_pk_mul_f32 v[2:3], v[2:3], v[20:21] op_sel_hi:[1,0]
	v_add_f32_e32 v19, 1.0, v19
	v_rcp_f32_e32 v22, v19
	v_mul_f32_e32 v19, 0xbfb8aa3b, v15
	v_exp_f32_e32 v19, v19
	v_pk_mul_f32 v[4:5], v[4:5], v[20:21] op_sel_hi:[1,0]
	s_andn2_b64 vcc, exec, s[42:43]
	v_add_f32_e32 v19, 1.0, v19
	v_rcp_f32_e32 v23, v19
	s_nop 0
	v_pk_mul_f32 v[14:15], v[14:15], v[22:23]
	s_nop 0
	v_pk_mul_f32 v[6:7], v[6:7], v[14:15]
	v_pk_mul_f32 v[14:15], v[16:17], v[20:21] op_sel_hi:[1,0]
	s_nop 0
	v_mul_f32_e32 v16, 0xbfb8aa3b, v14
	v_mul_f32_e32 v17, 0xbfb8aa3b, v15
	v_exp_f32_e32 v16, v16
	v_exp_f32_e32 v17, v17
	v_add_f32_e32 v16, 1.0, v16
	v_add_f32_e32 v17, 1.0, v17
	v_rcp_f32_e32 v16, v16
	v_rcp_f32_e32 v17, v17
	s_nop 0
	v_pk_mul_f32 v[14:15], v[14:15], v[16:17]
	s_nop 0
	v_pk_mul_f32 v[8:9], v[8:9], v[14:15]
	v_mul_f32_e32 v14, 0xbfb8aa3b, v10
	v_mul_f32_e32 v15, 0xbfb8aa3b, v11
	v_exp_f32_e32 v14, v14
	v_exp_f32_e32 v15, v15
	v_add_f32_e32 v14, 1.0, v14
	v_add_f32_e32 v15, 1.0, v15
	v_rcp_f32_e32 v14, v14
	v_rcp_f32_e32 v15, v15
	s_nop 0
	v_pk_mul_f32 v[10:11], v[10:11], v[14:15]
	s_nop 0
	v_pk_mul_f32 v[10:11], v[2:3], v[10:11]
	v_pk_mul_f32 v[2:3], v[12:13], v[20:21] op_sel_hi:[1,0]
	s_nop 0
	v_mul_f32_e32 v12, 0xbfb8aa3b, v2
	v_mul_f32_e32 v13, 0xbfb8aa3b, v3
	v_exp_f32_e32 v12, v12
	v_exp_f32_e32 v13, v13
	v_add_f32_e32 v12, 1.0, v12
	v_add_f32_e32 v13, 1.0, v13
	v_rcp_f32_e32 v12, v12
	v_rcp_f32_e32 v13, v13
	s_nop 0
	v_pk_mul_f32 v[2:3], v[2:3], v[12:13]
	s_nop 0
	v_pk_mul_f32 v[12:13], v[4:5], v[2:3]
	v_cvt_pk_bf16_f32 v2, v6, v7
	v_cvt_pk_bf16_f32 v3, v8, v9
	v_cvt_pk_bf16_f32 v4, v10, v11
	v_cvt_pk_bf16_f32 v5, v12, v13
	v_mad_i64_i32 v[6:7], s[6:7], v18, s4, v[142:143]
	global_store_dwordx4 v[6:7], v[2:5], off
	s_cbranch_vccnz .LBB0_1147
	s_andn2_b64 vcc, exec, s[0:1]
	s_cbranch_vccnz .LBB0_1146
	s_barrier
	s_branch .LBB0_1146
